# stagger-24 stack + the static first sample item bypasses the queue hand-off (thread-0 block, LDS slot, two s_barriers)
# baseline (speedup 1.0000x reference)
; __device__ __forceinline__ void p_mixer(const Args& a, int l, LAS unsigned char* lds, int tid, int lane, int wave, int bid, int G) {
;     ...
;         if (!prompt_done && (!qfirst || pulled >= 1 || queue_empty)) {
; #pragma unroll 1
;             for (int it = bid; it < N_AP; it += G) { asm volatile("" : "+v"(tid)); lane = tid & 63; attn_prompt_item(a, l, it, lds, tid, lane, wave); }
;             prompt_done = true; continue;
;         }
;         if (queue_empty) break;
;         if (threadIdx.x == 0) slot[0] = __hip_atomic_fetch_add(head, 1u, __ATOMIC_RELAXED, __HIP_MEMORY_SCOPE_AGENT);
;         __syncthreads();
;         const int q = (int)slot[0];
;         __syncthreads();
;         if (q >= N_AS + N_CV) { queue_empty = true; continue; }
;         ++pulled;
;         asm volatile("" : "+v"(tid)); lane = tid & 63;
;         if (q < N_AS) attn_sample_item(a, l, q, lds, tid, lane, wave);
;         else conv_item(a, l, q - N_AS, lane, wave);
.LBB0_445:
	s_and_b64 vcc, exec, s[0:1]
	s_cbranch_vccz .LBB0_440
	s_xor_b64 s[6:7], s[68:69], -1
	s_mov_b64 s[0:1], -1
	v_readfirstlane_b32 s4, v0
	s_andn2_b64 vcc, exec, s[6:7]
	s_cbranch_vccnz .LBB0_534
	s_cmp_lg_u32 s42, 0x100
	s_cbranch_scc1 .Lq1b_dyn
	s_cmp_lg_u32 s93, 0
	s_cbranch_scc1 .Lq1b_dyn
	s_bitcmp0_b32 s71, 3
	s_cbranch_scc1 .Lq1b_dyn
	s_lshr_b32 s4, s71, 4
	s_lshl_b32 s4, s4, 3
	s_and_b32 s5, s71, 7
	s_or_b32 s4, s4, s5
	v_mov_b32_e32 v0, s4
	s_movk_i32 s0, 0x18f
	s_mov_b64 s[68:69], -1
	s_branch .Lq1b_join
.Lq1b_dyn:
	s_mov_b64 s[0:1], exec
	v_readlane_b32 s4, v253, 2
	v_readlane_b32 s5, v253, 3
	s_and_b64 s[4:5], s[0:1], s[4:5]
	s_mov_b64 exec, s[4:5]
	s_cbranch_execz .LBB0_451
	s_mov_b64 s[6:7], exec
	v_mbcnt_lo_u32_b32 v0, s6, 0
	v_mbcnt_hi_u32_b32 v0, s7, v0
	v_cmp_eq_u32_e32 vcc, 0, v0
	s_and_saveexec_b64 s[4:5], vcc
	s_cbranch_execz .LBB0_450
	s_bcnt1_i32_b64 s6, s[6:7]
	v_readlane_b32 s2, v255, 15
	v_mov_b32_e32 v1, s6
	v_readlane_b32 s3, v255, 16
	s_cmp_lg_u32 s42, 0x100
	s_cbranch_scc1 .Lq_dyn
	s_cmp_lg_u32 s93, 0
	s_cbranch_scc1 .Lq_dyn128
	s_bitcmp0_b32 s71, 3
	s_cbranch_scc1 .Lq_dyn128
	s_lshr_b32 s6, s71, 4
	s_lshl_b32 s6, s6, 3
	s_and_b32 s7, s71, 7
	s_or_b32 s6, s6, s7
	v_mov_b32_e32 v1, s6
	s_branch .LBB0_450

; __device__ __forceinline__ void conv_item(const Args& a, int l, int it, int lane, int wave) {
;     const bf16_t* proj = (const bf16_t*)(a.ws + WS_PROJ); bf16_t* Y = (bf16_t*)(a.ws + WS_H);
;     const int t0 = it * 64 + wave * 8, ch = lane * 8;
;     const float* cw = a.in[11] + (size_t)l * 3 * 512 + ch;
;     float w0[8], w1[8], w2[8];
;     { const f32x4 a0 = *(const f32x4*)(cw), a1 = *(const f32x4*)(cw + 4), b0 = *(const f32x4*)(cw + 512), b1 = *(const f32x4*)(cw + 516), c0 = *(const f32x4*)(cw + 1024), c1 = *(const f32x4*)(cw + 1028);
;       w0[0] = a0.x; w0[1] = a0.y; w0[2] = a0.z; w0[3] = a0.w; w0[4] = a1.x; w0[5] = a1.y; w0[6] = a1.z; w0[7] = a1.w;
;       w1[0] = b0.x; w1[1] = b0.y; w1[2] = b0.z; w1[3] = b0.w; w1[4] = b1.x; w1[5] = b1.y; w1[6] = b1.z; w1[7] = b1.w;
;       w2[0] = c0.x; w2[1] = c0.y; w2[2] = c0.z; w2[3] = c0.w; w2[4] = c1.x; w2[5] = c1.y; w2[6] = c1.z; w2[7] = c1.w; }
;     u32x4 uw[8], gw[8];
; #pragma unroll
;     for (int i = 0; i < 8; ++i) { uw[i] = *(const u32x4*)(proj + (size_t)(t0 + i) * PO2 + C_U + ch); gw[i] = *(const u32x4*)(proj + (size_t)(t0 + i) * PO2 + C_GZ + ch); }
;     float u2[8], u1[8];
;     if (t0 < MP) {
;         if ((t0 & (LP - 1)) == 0) {
; #pragma unroll
;             for (int i = 0; i < 8; ++i) { u2[i] = 0.f; u1[i] = 0.f; }
;         } else {
;             unpack8(*(const u32x4*)(proj + (size_t)(t0 - 2) * PO2 + C_U + ch), u2);
;             unpack8(*(const u32x4*)(proj + (size_t)(t0 - 1) * PO2 + C_U + ch), u1);
;         }
;     } else {
;         const int n = (t0 - MP) >> 3;
;         const float* sc = a.in[4] + ((size_t)(l * NSB + n) * 2) * 512 + ch;
;         const f32x4 a0 = *(const f32x4*)(sc), a1 = *(const f32x4*)(sc + 4), b0 = *(const f32x4*)(sc + 512), b1 = *(const f32x4*)(sc + 516);
;         u2[0] = a0.x; u2[1] = a0.y; u2[2] = a0.z; u2[3] = a0.w; u2[4] = a1.x; u2[5] = a1.y; u2[6] = a1.z; u2[7] = a1.w;
; __device__ __forceinline__ void p_mixer(const Args& a, int l, LAS unsigned char* lds, int tid, int lane, int wave, int bid, int G) {
;     ...
;         if (q >= N_AS + N_CV) { queue_empty = true; continue; }
;         ++pulled;
;         asm volatile("" : "+v"(tid)); lane = tid & 63;
;         if (q < N_AS) attn_sample_item(a, l, q, lds, tid, lane, wave);
;         else conv_item(a, l, q - N_AS, lane, wave);
.Lq1b_join:
	v_cmp_lt_i32_e32 vcc, s0, v0
	v_readfirstlane_b32 s36, v0
	s_cbranch_vccnz .LBB0_533
	s_mov_b64 s[0:1], -1
	v_and_b32_e32 v108, 63, v130
	s_cmpk_gt_i32 s36, 0x7f
	v_lshlrev_b32_e32 v109, 3, v108
	v_lshlrev_b32_e32 v110, 4, v108
	s_cbranch_scc0 .LBB0_503
	s_lshl_b32 s0, s36, 6
	v_readlane_b32 s1, v255, 17
	v_readlane_b32 s2, v255, 31
	s_add_i32 s0, s1, s0
	v_lshlrev_b32_e32 v172, 5, v108
	v_readlane_b32 s3, v255, 32
	s_ashr_i32 s1, s0, 31
	s_mul_i32 s4, s0, 0x1200
	v_lshl_add_u64 v[8:9], s[2:3], 0, v[172:173]
	v_lshl_add_u64 v[10:11], v[8:9], 0, s[26:27]
	v_add_co_u32_e32 v8, vcc, 0x1000, v8
	s_mul_hi_i32 s5, s0, 0x1200
	s_add_u32 s4, s74, s4
	v_addc_co_u32_e32 v9, vcc, 0, v9, vcc
	s_addc_u32 s5, s75, s5
	s_or_b32 s34, s0, 1
	global_load_dwordx4 v[0:3], v172, s[2:3] offset:16
	global_load_dwordx4 v[12:15], v172, s[2:3]
	global_load_dwordx4 v[4:7], v172, s[2:3] offset:2064
	global_load_dwordx4 v[16:19], v172, s[2:3] offset:2048
	global_load_dwordx4 v[20:23], v[8:9], off
	s_nop 0
	global_load_dwordx4 v[8:11], v[10:11], off offset:16
	s_nop 0
	global_load_dwordx4 v[84:87], v110, s[4:5]
	global_load_dwordx4 v[80:83], v110, s[4:5] offset:1024
	s_mul_i32 s4, s34, 0x1200
	s_mul_hi_i32 s5, s34, 0x1200
	s_add_u32 s4, s74, s4
	s_addc_u32 s5, s75, s5
	s_or_b32 s2, s0, 2
	global_load_dwordx4 v[76:79], v110, s[4:5]
	global_load_dwordx4 v[72:75], v110, s[4:5] offset:1024
	s_mul_i32 s4, s2, 0x1200
	s_mul_hi_i32 s5, s2, 0x1200
	s_add_u32 s4, s74, s4
	s_addc_u32 s5, s75, s5
	s_or_b32 s14, s0, 3
	global_load_dwordx4 v[68:71], v110, s[4:5]
	global_load_dwordx4 v[64:67], v110, s[4:5] offset:1024
	s_mul_i32 s4, s14, 0x1200
	s_mul_hi_i32 s5, s14, 0x1200
	s_add_u32 s4, s74, s4
	s_addc_u32 s5, s75, s5
	s_or_b32 s12, s0, 4
	global_load_dwordx4 v[60:63], v110, s[4:5]
	global_load_dwordx4 v[56:59], v110, s[4:5] offset:1024
	s_mul_i32 s4, s12, 0x1200
	s_mul_hi_i32 s5, s12, 0x1200
	s_add_u32 s4, s74, s4
	s_addc_u32 s5, s75, s5
	s_or_b32 s10, s0, 5
	global_load_dwordx4 v[52:55], v110, s[4:5]
	global_load_dwordx4 v[48:51], v110, s[4:5] offset:1024
	s_mul_i32 s4, s10, 0x1200
	s_mul_hi_i32 s5, s10, 0x1200
	s_add_u32 s4, s74, s4
	s_addc_u32 s5, s75, s5
	s_or_b32 s8, s0, 6
	global_load_dwordx4 v[44:47], v110, s[4:5]
	global_load_dwordx4 v[40:43], v110, s[4:5] offset:1024
	s_mul_i32 s4, s8, 0x1200
	s_mul_hi_i32 s5, s8, 0x1200
	s_add_u32 s4, s74, s4
	s_addc_u32 s5, s75, s5
	global_load_dwordx4 v[36:39], v110, s[4:5]
	global_load_dwordx4 v[32:35], v110, s[4:5] offset:1024
	s_or_b32 s4, s0, 7
	s_mul_i32 s6, s4, 0x1200
	s_mul_hi_i32 s5, s4, 0x1200
	s_add_u32 s6, s74, s6
	s_addc_u32 s7, s75, s5
	global_load_dwordx4 v[28:31], v110, s[6:7]
	global_load_dwordx4 v[24:27], v110, s[6:7] offset:1024
	s_cmpk_gt_i32 s0, 0x3fff
	s_cselect_b64 s[6:7], -1, 0
	s_mov_b64 s[20:21], -1
	s_and_b64 vcc, exec, s[6:7]
	v_lshlrev_b32_e32 v104, 2, v109
	s_cbranch_vccz .LBB0_455
	s_add_i32 s5, s0, 0xffffc000
	s_lshr_b32 s5, s5, 2
	v_readlane_b32 s3, v255, 18
	s_add_i32 s86, s5, s3
	v_readlane_b32 s16, v253, 4
	s_lshl_b64 s[38:39], s[86:87], 11
	v_readlane_b32 s20, v253, 8
	v_readlane_b32 s24, v253, 12
	v_readlane_b32 s21, v253, 9
	v_readlane_b32 s25, v253, 13
	s_add_u32 s20, s24, s38
	s_addc_u32 s21, s25, s39
	s_nop 1
	global_load_dwordx4 v[100:103], v104, s[20:21]
	global_load_dwordx4 v[96:99], v104, s[20:21] offset:16
	global_load_dwordx4 v[92:95], v104, s[20:21] offset:2048
	global_load_dwordx4 v[88:91], v104, s[20:21] offset:2064
	v_readlane_b32 s26, v253, 14
	v_readlane_b32 s27, v253, 15
	v_readlane_b32 s17, v253, 5
	v_readlane_b32 s18, v253, 6
	v_readlane_b32 s19, v253, 7
	v_readlane_b32 s22, v253, 10
	v_readlane_b32 s23, v253, 11
	v_readlane_b32 s28, v253, 16
	v_readlane_b32 s29, v253, 17
	v_readlane_b32 s30, v253, 18
	v_readlane_b32 s31, v253, 19
	s_mov_b64 s[26:27], 0x1000
	s_mov_b64 s[20:21], 0
